# attention phase: static priority 2 for the map-0 waves (one of the two waves per SIMD) so the SIMD-mates issue their MFMA batches one after the other; reset at next phase; on top of v111
# baseline (speedup 1.0000x reference)
.LBB0_1112:
	s_cmp_lt_i32 s28, 11
	s_cselect_b64 s[2:3], -1, 0
	s_and_b64 s[2:3], s[2:3], s[0:1]
	s_andn2_b64 vcc, exec, s[2:3]
	s_cbranch_vccnz .LBB0_1140
	s_cmpk_gt_i32 s76, 0x3ff
	s_cbranch_scc1 .LBB0_1139
	s_add_u32 s72, s24, 0x1e200000
	s_addc_u32 s73, s25, 0
	s_add_u32 s74, s24, 0x20200000
	s_addc_u32 s75, s25, 0
	s_add_u32 s4, s24, 0x16a00000
	s_addc_u32 s5, s25, 0
	s_add_u32 s8, s24, 0x22200000
	s_addc_u32 s9, s25, 0
	s_lshr_b32 s11, s77, 7
	s_lshr_b32 s1, s77, 5
	s_bfe_u32 s0, s77, 0x10006
	s_and_b32 s26, s1, 12
	s_lshl_b32 s1, s11, 15
	s_lshl_b32 s11, s11, 12
	s_add_i32 s79, s11, 0
	s_lshl_b32 s11, s0, 10
	v_readlane_b32 s59, v250, 2
	s_lshr_b32 s7, s77, 8
	s_cmp_eq_u32 s7, 0
	s_cbranch_scc0 .Latt_prio_lo
	s_setprio 2
.Latt_prio_lo:
	s_add_i32 s79, s79, s11
	s_lshl_b32 s11, s59, 10
	s_add_i32 s54, 0, 0x10000
	s_bfe_u32 s10, s77, 0x20006
	s_add_i32 s27, 0, 0x20000
	s_add_i32 s80, s54, s11
	s_lshl_b32 s11, s7, 10
	s_lshl_b32 s78, s10, 4
	s_lshl_b32 s50, s7, 7
	s_lshl_b32 s55, s7, 4
	s_add_i32 s81, s27, s11
	s_lshl_b32 s11, s10, 14
	s_cmp_lt_u32 s10, 2
	s_mov_b32 s10, 0x8000
	s_cselect_b32 s10, s10, 0x10000
	s_add_i32 s11, s11, 0
	s_add_i32 s56, s11, s10
	s_cmp_eq_u32 s7, 1
	s_cselect_b64 s[10:11], -1, 0
	s_add_u32 s14, s24, 0x22204000
	s_addc_u32 s15, s25, 0
	s_cmpk_lt_u32 s77, 0x100
	s_cselect_b64 s[16:17], -1, 0
	s_bfe_u32 s92, s76, 0x30003
	s_lshl_b32 s7, s92, 22
	s_add_u32 s7, s74, s7
	s_addc_u32 s30, s75, 0
	s_lshl_b32 s31, s76, 5
	s_and_b32 s51, s31, 0x1800
	s_lshl_b32 s31, s51, 1
	s_add_u32 s48, s7, s31
	s_addc_u32 s49, s30, 0
	s_lshl_b32 s7, s51, 12
	s_add_u32 s7, s72, s7
	v_and_b32_e32 v0, 0x300, v226
	s_addc_u32 s40, s73, 0
	s_lshl_b32 s57, s92, 9
	v_add_u32_e32 v0, s57, v0
	s_movk_i32 s30, 0xff
	v_and_or_b32 v0, v226, s30, v0
	v_lshlrev_b32_e32 v0, 2, v0
	global_load_dword v1, v0, s[8:9]
	v_lshrrev_b32_e32 v32, 5, v227
	v_lshl_or_b32 v0, s0, 1, v32
	v_and_b32_e32 v2, 31, v226
	v_bitop3_b32 v2, v0, v2, s26 bitop3:0x36
	v_lshlrev_b32_e32 v0, 12, v0
	v_lshlrev_b32_e32 v33, 4, v2
	v_lshrrev_b32_e32 v34, 3, v227
	v_or3_b32 v132, v0, s1, v33
	v_lshl_or_b32 v0, s59, 3, v34
	v_lshrrev_b32_e32 v2, 1, v0
	v_xor_b32_e32 v2, v2, v226
	v_lshlrev_b32_e32 v2, 4, v2
	s_add_u32 s52, s7, s57
	v_and_b32_e32 v35, 0x70, v2
	s_addc_u32 s53, s40, 0
	v_lshl_or_b32 v134, v0, 14, v35
	v_mov_b32_e32 v0, 0
	s_add_u32 s7, s18, s57
	v_lshl_add_u32 v151, v226, 2, s27
	v_mov_b32_e32 v135, v0
	s_addc_u32 s27, s19, 0
	s_and_b32 s26, s77, 0xffffff00
	v_mov_b32_e32 v133, v0
	v_lshl_add_u64 v[4:5], s[48:49], 0, v[134:135]
	s_mov_b64 s[30:31], 0x300000
	s_mov_b64 s[34:35], 0x200000
	s_mov_b64 s[36:37], 0x100000
	s_add_u32 s26, s7, s26
	v_and_b32_e32 v2, 48, v227
	v_mov_b32_e32 v3, v0
	v_lshl_add_u64 v[20:21], v[4:5], 0, s[30:31]
	v_lshl_add_u64 v[22:23], v[4:5], 0, s[34:35]
	v_lshl_add_u64 v[24:25], v[4:5], 0, s[36:37]
	v_lshl_add_u64 v[4:5], s[52:53], 0, v[132:133]
	s_mov_b64 s[40:41], 0x24000
	s_mov_b64 s[42:43], 0x20000
	s_mov_b64 s[46:47], 0x4000
	s_addc_u32 s27, s27, 0
	s_and_b32 s7, s76, 7
	v_lshl_add_u64 v[26:27], v[4:5], 0, s[40:41]
	v_lshl_add_u64 v[28:29], v[4:5], 0, s[42:43]
	v_lshl_add_u64 v[30:31], v[4:5], 0, s[46:47]
	v_lshl_add_u64 v[4:5], s[26:27], 0, v[2:3]
	s_xor_b32 s26, s7, 31
	s_ashr_i32 s27, s76, 8
	s_xor_b32 s57, s7, 23
	s_or_b32 s58, s7, 8
	s_cmp_eq_u32 s27, 2
	s_cselect_b32 s57, s57, s58
	s_cmp_eq_u32 s27, 1
	s_cselect_b32 s7, s7, s57
	s_cmpk_lt_u32 s76, 0x100
	s_cselect_b32 s7, s26, s7
	s_lshl_b32 s26, s7, 6
	s_or_b32 s87, s26, s78
	v_and_b32_e32 v150, 15, v226
	s_add_i32 s93, s87, s51
	v_or_b32_e32 v6, s93, v150
	v_mov_b32_e32 v7, v0
	v_lshlrev_b64 v[6:7], 12, v[6:7]
	v_lshl_add_u64 v[16:17], v[4:5], 0, v[6:7]
	s_mov_b32 m0, s79
	s_add_i32 s77, s79, 0x800
	global_load_dwordx4 v[4:7], v[16:17], off
	s_add_i32 s82, s79, 0x4000
	s_add_i32 s83, s79, 0x4800
	s_add_i32 s84, s80, 0x2000
	s_add_i32 s85, s80, 0x4000
	s_add_i32 s86, s80, 0x6000
	v_lshl_add_u64 v[136:137], s[20:21], 0, v[2:3]
	s_add_i32 s69, s7, 1
	s_lshl_b32 s7, s59, 17
	s_lshl_b32 s0, s0, 13
	s_or_b32 s0, s1, s0
	s_mov_b32 s51, 0
	v_lshl_add_u32 v152, v227, 4, s56
	v_lshl_add_u32 v157, v150, 7, s54
	v_mov_b32_e32 v139, v0
	v_mov_b32_e32 v141, v0
	s_waitcnt vmcnt(0)
	ds_write_b32 v151, v1
	global_load_dwordx4 v[8:11], v[16:17], off offset:64
	global_load_dwordx4 v[12:15], v[16:17], off offset:128
	s_nop 0
	global_load_dwordx4 v[16:19], v[16:17], off offset:192
	v_lshrrev_b32_e32 v1, 4, v227
	global_load_lds_dwordx4 v132, s[52:53]
	s_mov_b32 m0, s77
	v_bitop3_b32 v2, s55, v150, v1 bitop3:0x36
	global_load_lds_dwordx4 v[30:31], off
	s_mov_b32 m0, s82
	v_lshlrev_b32_e32 v153, 4, v2
	global_load_lds_dwordx4 v[28:29], off
	s_mov_b32 m0, s83
	s_mov_b64 s[20:21], 0x40000
	global_load_lds_dwordx4 v[26:27], off
	s_mov_b32 m0, s80
	s_mov_b64 s[56:57], 0x60000
	global_load_lds_dwordx4 v134, s[48:49]
	s_mov_b32 m0, s84
	s_mov_b64 s[58:59], 0x64000
	global_load_lds_dwordx4 v[24:25], off
	s_mov_b32 m0, s85
	v_lshrrev_b32_e32 v24, 1, v226
	global_load_lds_dwordx4 v[22:23], off
	s_mov_b32 m0, s86
	v_or_b32_e32 v23, s55, v1
	global_load_lds_dwordx4 v[20:21], off
	v_bitop3_b32 v2, v23, v150, 4 bitop3:0x36
	v_lshlrev_b32_e32 v154, 4, v2
	v_bitop3_b32 v2, v23, v150, 8 bitop3:0x36
	v_lshlrev_b32_e32 v21, 1, v226
	v_and_b32_e32 v22, 3, v226
	v_bfe_u32 v25, v226, 1, 3
	v_lshlrev_b32_e32 v155, 4, v2
	v_bitop3_b32 v2, v23, v150, 12 bitop3:0x36
	v_lshlrev_b32_e32 v20, 3, v1
	v_and_or_b32 v21, v21, 24, v22
	v_lshlrev_b32_e32 v22, 2, v1
	v_lshlrev_b32_e32 v156, 4, v2
	v_bitop3_b32 v2, v1, v24, 7 bitop3:0x78
	v_bitop3_b32 v1, v1, v25, 4 bitop3:0x36
	v_lshlrev_b32_e32 v159, 4, v1
	v_lshlrev_b32_e32 v1, 14, v34
	v_or3_b32 v138, s7, v1, v35
	v_lshlrev_b32_e32 v1, 12, v32
	v_or3_b32 v140, s0, v1, v33
	v_mbcnt_lo_u32_b32 v1, -1, 0
	v_lshlrev_b32_e32 v158, 4, v2
	v_lshl_add_u32 v160, v21, 9, 0
	v_sub_u32_e32 v161, v20, v150
	s_mov_b64 s[54:55], 0x44000
	s_mov_b64 s[60:61], 0x80
	s_mov_b64 s[62:63], 0x100080
	s_mov_b64 s[64:65], 0x200080
	s_mov_b64 s[66:67], 0x300080
	s_lshl_b32 s68, s50, 1
	v_lshlrev_b32_e32 v142, 1, v20
	v_mov_b32_e32 v162, 0x3727c5ac
	s_mov_b32 s88, 0xf800000
	v_mov_b32_e32 v163, 0x260
	s_mov_b32 s89, 0x3f24fd5c
	v_lshlrev_b32_e32 v144, 1, v22
	v_mbcnt_hi_u32_b32 v164, -1, v1
	s_branch .LBB0_1116

.LBB0_1194:
	s_setprio 0
	s_cmp_lt_i32 s28, 12
	s_cselect_b64 s[2:3], -1, 0
	s_and_b64 s[8:9], s[2:3], s[0:1]
	s_andn2_b64 vcc, exec, s[8:9]
	s_cbranch_vccnz .LBB0_1269
	s_cmpk_gt_i32 s6, 0xff
	v_readfirstlane_b32 s1, v226
	s_cbranch_scc1 .LBB0_1269
	s_add_u32 s11, s24, 0x16a00000
	s_addc_u32 s54, s25, 0
	s_add_u32 s55, s24, 0x12200000
	s_addc_u32 s56, s25, 0
	s_lshr_b32 s2, s1, 6
	s_lshl_b32 s0, s2, 3
	s_add_i32 s3, s0, 64
	v_lshrrev_b32_e32 v8, 3, v227
	v_or_b32_e32 v0, s3, v8
	v_lshrrev_b32_e32 v3, 1, v0
	v_xor_b32_e32 v3, v3, v226
	s_and_b32 s4, s3, 0xfffe0
	v_lshlrev_b32_e32 v1, 1, v0
	s_lshr_b32 s3, s1, 5
	v_bfe_u32 v2, v227, 3, 2
	v_lshlrev_b32_e32 v3, 4, v3
	v_and_b32_e32 v1, 24, v1
	v_and_or_b32 v2, s3, 4, v2
	v_and_b32_e32 v9, 0x70, v3
	v_or3_b32 v1, s4, v1, v2
	v_lshl_or_b32 v130, v0, 12, v9
	v_or_b32_e32 v0, s0, v8
	s_ashr_i32 s58, s6, 31
	v_lshl_or_b32 v128, v1, 12, v9
	s_and_b32 s3, s0, 0xfffe0
	v_lshlrev_b32_e32 v1, 1, v0
	s_lshr_b32 s0, s58, 29
	v_and_b32_e32 v1, 24, v1
	s_add_i32 s0, s6, s0
	v_or3_b32 v1, s3, v1, v2
	s_and_b32 s3, s0, -8
	s_sub_i32 s3, s6, s3
	s_lshr_b32 s52, s1, 8
	s_lshl_b32 s57, s2, 10
	s_lshl_b32 s5, s3, 5
	s_ashr_i32 s0, s0, 3
	s_mul_i32 s4, s3, 33
	s_cmp_lt_i32 s3, 0
	s_cselect_b32 s3, s4, s5
	s_add_i32 s0, s3, s0
	s_ashr_i32 s3, s0, 31
	s_lshr_b32 s3, s3, 26
	s_add_i32 s3, s0, s3
	s_ashr_i32 s4, s3, 6
	s_andn2_b32 s3, s3, 63
	s_sub_i32 s3, s0, s3
	s_bfe_i32 s0, s3, 0x80000
	s_bfe_u32 s0, s0, 0x3000c
	s_add_i32 s5, s3, s0
	s_bfe_i32 s0, s5, 0x80000
	s_and_b32 s5, s5, 0xf8
	s_sub_i32 s3, s3, s5
	s_lshl_b32 s4, s4, 3
	s_sext_i32_i8 s3, s3
	s_add_i32 s4, s4, s3
	s_sext_i32_i16 s0, s0
	s_ashr_i32 s5, s4, 31
	s_lshr_b32 s0, s0, 3
	s_lshl_b64 s[14:15], s[4:5], 20
	s_add_u32 s42, s11, s14
	v_lshrrev_b32_e32 v2, 1, v0
	s_addc_u32 s43, s54, s15
	s_bfe_i64 s[14:15], s[0:1], 0x100000
	v_xor_b32_e32 v2, v2, v226
	s_lshl_b64 s[14:15], s[14:15], 20
	v_lshlrev_b32_e32 v2, 4, v2
	s_add_u32 s46, s55, s14
	v_and_b32_e32 v10, 0x70, v2
	s_addc_u32 s47, s56, s15
	s_add_i32 s5, s57, 0
	v_lshl_or_b32 v132, v1, 12, v10
	s_add_i32 m0, s5, 0x10000
	v_lshl_or_b32 v134, v0, 12, v10
	global_load_lds_dwordx4 v132, s[46:47]
	s_add_i32 m0, s5, 0x12000
	s_add_u32 s14, s46, 0x80000
	global_load_lds_dwordx4 v128, s[46:47]
	s_addc_u32 s15, s47, 0
	s_add_i32 m0, s5, 0x14000
	s_add_i32 s59, s5, 0x2000
	global_load_lds_dwordx4 v132, s[14:15]
	s_add_i32 m0, s5, 0x16000
	v_mov_b32_e32 v133, 0
	global_load_lds_dwordx4 v128, s[14:15]
	s_mov_b32 m0, s5
	s_add_u32 s14, s42, 0x80000
	global_load_lds_dwordx4 v134, s[42:43]
	s_mov_b32 m0, s59
	s_addc_u32 s15, s43, 0
	s_add_i32 s60, s5, 0x4000
	global_load_lds_dwordx4 v130, s[42:43]
	s_mov_b32 m0, s60
	s_add_i32 s61, s5, 0x6000
	global_load_lds_dwordx4 v134, s[14:15]
	s_mov_b32 m0, s61
	v_mov_b32_e32 v129, v133
	global_load_lds_dwordx4 v130, s[14:15]
	v_mov_b32_e32 v135, v133
	v_mov_b32_e32 v131, v133
	s_cmp_eq_u32 s52, 1
	v_lshl_add_u64 v[6:7], s[46:47], 0, v[132:133]
	v_lshl_add_u64 v[4:5], s[46:47], 0, v[128:129]
	v_lshl_add_u64 v[0:1], s[42:43], 0, v[134:135]
	s_cselect_b64 s[14:15], -1, 0
	s_cmp_lg_u32 s52, 1
	v_lshl_add_u64 v[2:3], s[42:43], 0, v[130:131]
	s_cbranch_scc1 .LBB0_1198
	s_barrier
